# mem_attn K/V staging: 8 loads in flight per thread instead of serialized load-wait-write loops (both instances)
# speedup vs baseline: 1.0299x; 1.0107x over previous
.LBB0_200:
	s_movk_i32 s4, 0x800
	v_cmp_gt_i32_e32 vcc, s4, v130
	s_waitcnt lgkmcnt(0)
	s_barrier
	s_and_saveexec_b64 s[6:7], vcc
	s_cbranch_execz .LBB0_205
	s_lshl_b32 s4, s40, 18
	s_add_u32 s4, s84, s4
	v_readlane_b32 s8, v254, 7
	s_addc_u32 s5, s85, 0
	s_lshl_b32 s8, s8, 1
	s_add_u32 s4, s4, s8
	v_readlane_b32 s8, v254, 9
	s_addc_u32 s5, s5, 0
	s_lshl_b32 s8, s8, 1
	s_add_u32 s4, s4, s8
	v_lshlrev_b32_e32 v5, 4, v130
	s_addc_u32 s5, s5, 0
	v_and_b32_e32 v134, 0x70, v5
	v_lshl_add_u64 v[2:3], s[4:5], 0, v[134:135]
	v_add_u32_e32 v4, 0, v134
	v_ashrrev_i32_e32 v12, 3, v130
	v_mov_b32_e32 v13, 0
	v_lshlrev_b64 v[8:9], 9, v[12:13]
	v_lshl_add_u64 v[8:9], v[2:3], 0, v[8:9]
	v_mad_u32_u24 v226, v12, s29, v4
	s_mov_b64 s[8:9], 0x8000
	global_load_dwordx4 v[178:181], v[8:9], off
	v_lshl_add_u64 v[8:9], v[8:9], 0, s[8:9]
	global_load_dwordx4 v[182:185], v[8:9], off
	v_lshl_add_u64 v[8:9], v[8:9], 0, s[8:9]
	global_load_dwordx4 v[186:189], v[8:9], off
	v_lshl_add_u64 v[8:9], v[8:9], 0, s[8:9]
	global_load_dwordx4 v[190:193], v[8:9], off
	s_lshl_b32 s4, s35, 18
	v_readlane_b32 s5, v254, 8
	s_or_b32 s4, s4, s5
	s_add_u32 s4, s31, s4
	s_addc_u32 s5, s59, 0
	v_readlane_b32 s8, v254, 10
	s_add_u32 s4, s4, s8
	s_addc_u32 s5, s5, 0
	v_and_b32_e32 v134, 0x1f0, v5
	v_lshl_add_u64 v[2:3], s[4:5], 0, v[134:135]
	v_add_u32_e32 v4, 0, v134
	v_ashrrev_i32_e32 v10, 5, v130
	v_mov_b32_e32 v11, 0
	v_lshlrev_b64 v[6:7], 9, v[10:11]
	v_lshl_add_u64 v[6:7], v[2:3], 0, v[6:7]
	v_mad_u32_u24 v227, v10, s36, v4
	s_mov_b64 s[8:9], 0x2000
	global_load_dwordx4 v[194:197], v[6:7], off
	v_lshl_add_u64 v[6:7], v[6:7], 0, s[8:9]
	global_load_dwordx4 v[198:201], v[6:7], off
	v_lshl_add_u64 v[6:7], v[6:7], 0, s[8:9]
	global_load_dwordx4 v[202:205], v[6:7], off
	v_lshl_add_u64 v[6:7], v[6:7], 0, s[8:9]
	global_load_dwordx4 v[206:209], v[6:7], off
	s_waitcnt vmcnt(7)
	ds_write_b128 v226, v[178:181]
	s_waitcnt vmcnt(6)
	ds_write_b128 v226, v[182:185] offset:9216
	s_waitcnt vmcnt(5)
	ds_write_b128 v226, v[186:189] offset:18432
	s_waitcnt vmcnt(4)
	ds_write_b128 v226, v[190:193] offset:27648
	s_waitcnt vmcnt(3)
	ds_write_b128 v227, v[194:197] offset:36864
	s_waitcnt vmcnt(2)
	ds_write_b128 v227, v[198:201] offset:45312
	s_waitcnt vmcnt(1)
	ds_write_b128 v227, v[202:205] offset:53760
	s_waitcnt vmcnt(0)
	ds_write_b128 v227, v[206:209] offset:62208

.LBB0_318:
	s_add_i32 s30, s22, 2
	s_add_u32 s37, s12, 0x80
	s_addc_u32 s23, s13, 0
	s_add_i32 s56, 0, 0x10000
	s_cmp_eq_u32 s5, s22
	s_cselect_b32 s23, s11, s23
	s_cselect_b32 s22, s10, s37
	v_add_u32_e32 v156, s56, v159
	s_cselect_b32 s69, s99, s25
	s_cselect_b32 s68, s98, s24
	s_add_i32 s37, 0, 0x14000
	ds_read_b128 v[152:155], v156
	ds_read_b128 v[178:181], v156 offset:1024
	ds_read_b128 v[182:185], v156 offset:2048
	ds_read_b128 v[186:189], v156 offset:3072
	v_add_u32_e32 v156, s37, v159
	ds_read_b128 v[190:193], v156
	ds_read_b128 v[194:197], v156 offset:1024
	ds_read_b128 v[198:201], v156 offset:2048
	ds_read_b128 v[202:205], v156 offset:3072
	v_lshl_add_u64 v[156:157], s[12:13], 0, v[148:149]
	s_add_i32 m0, s45, 0xc000
	ds_read_b128 v[206:209], v161
	ds_read_b128 v[210:213], v161 offset:1024
	ds_read_b128 v[214:217], v161 offset:2048
	ds_read_b128 v[218:221], v161 offset:3072
	ds_read_b128 v[222:225], v161 offset:4096
	ds_read_b128 v[226:229], v161 offset:5120
	ds_read_b128 v[230:233], v161 offset:6144
	ds_read_b128 v[234:237], v161 offset:7168
	global_load_lds_dwordx4 v[156:157], off
	v_lshl_add_u64 v[156:157], s[12:13], 0, v[150:151]
	s_add_i32 m0, s45, 0xe000
	s_nop 0
	global_load_lds_dwordx4 v[156:157], off
	s_waitcnt vmcnt(8)
	s_waitcnt lgkmcnt(0)
	s_barrier
	s_setprio 1
	s_waitcnt lgkmcnt(0)
	v_mfma_f32_16x16x32_bf16 v[126:129], v[152:155], v[206:209], v[126:129]
	v_mfma_f32_16x16x32_bf16 v[122:125], v[182:185], v[206:209], v[122:125]
	v_mfma_f32_16x16x32_bf16 v[110:113], v[152:155], v[214:217], v[110:113]
	v_mfma_f32_16x16x32_bf16 v[106:109], v[182:185], v[214:217], v[106:109]
	v_mfma_f32_16x16x32_bf16 v[94:97], v[152:155], v[222:225], v[94:97]
	v_mfma_f32_16x16x32_bf16 v[90:93], v[182:185], v[222:225], v[90:93]
	v_mfma_f32_16x16x32_bf16 v[78:81], v[152:155], v[230:233], v[78:81]
	v_mfma_f32_16x16x32_bf16 v[74:77], v[182:185], v[230:233], v[74:77]
	v_mfma_f32_16x16x32_bf16 v[126:129], v[178:181], v[210:213], v[126:129]
	v_mfma_f32_16x16x32_bf16 v[122:125], v[186:189], v[210:213], v[122:125]
	v_mfma_f32_16x16x32_bf16 v[110:113], v[178:181], v[218:221], v[110:113]
	v_mfma_f32_16x16x32_bf16 v[106:109], v[186:189], v[218:221], v[106:109]
	v_mfma_f32_16x16x32_bf16 v[94:97], v[178:181], v[226:229], v[94:97]
	v_mfma_f32_16x16x32_bf16 v[90:93], v[186:189], v[226:229], v[90:93]
	v_mfma_f32_16x16x32_bf16 v[78:81], v[178:181], v[234:237], v[78:81]
	v_mfma_f32_16x16x32_bf16 v[74:77], v[186:189], v[234:237], v[74:77]
	s_setprio 0
	s_setprio 1
	v_mfma_f32_16x16x32_bf16 v[118:121], v[190:193], v[206:209], v[118:121]
	v_mfma_f32_16x16x32_bf16 v[114:117], v[198:201], v[206:209], v[114:117]
	v_mfma_f32_16x16x32_bf16 v[102:105], v[190:193], v[214:217], v[102:105]
	v_mfma_f32_16x16x32_bf16 v[98:101], v[198:201], v[214:217], v[98:101]
	v_mfma_f32_16x16x32_bf16 v[86:89], v[190:193], v[222:225], v[86:89]
	v_mfma_f32_16x16x32_bf16 v[82:85], v[198:201], v[222:225], v[82:85]
	v_mfma_f32_16x16x32_bf16 v[70:73], v[190:193], v[230:233], v[70:73]
	v_mfma_f32_16x16x32_bf16 v[66:69], v[198:201], v[230:233], v[66:69]
	v_mfma_f32_16x16x32_bf16 v[118:121], v[194:197], v[210:213], v[118:121]
	v_mfma_f32_16x16x32_bf16 v[114:117], v[202:205], v[210:213], v[114:117]
	v_mfma_f32_16x16x32_bf16 v[102:105], v[194:197], v[218:221], v[102:105]
	v_mfma_f32_16x16x32_bf16 v[98:101], v[202:205], v[218:221], v[98:101]
	s_setprio 2
	s_barrier
	v_mfma_f32_16x16x32_bf16 v[86:89], v[194:197], v[226:229], v[86:89]
	v_mfma_f32_16x16x32_bf16 v[82:85], v[202:205], v[226:229], v[82:85]
	v_mfma_f32_16x16x32_bf16 v[70:73], v[194:197], v[234:237], v[70:73]
	v_mfma_f32_16x16x32_bf16 v[66:69], v[202:205], v[234:237], v[66:69]
	s_setprio 0
	s_add_i32 s56, s56, s26
	v_lshl_add_u64 v[156:157], s[68:69], 0, v[134:135]
	s_mov_b32 m0, s56
	ds_read_b128 v[206:209], v161 offset:16384
	ds_read_b128 v[210:213], v161 offset:17408
	ds_read_b128 v[214:217], v161 offset:18432
	ds_read_b128 v[218:221], v161 offset:19456
	ds_read_b128 v[222:225], v161 offset:20480
	ds_read_b128 v[226:229], v161 offset:21504
	ds_read_b128 v[230:233], v161 offset:22528
	ds_read_b128 v[234:237], v161 offset:23552
	global_load_lds_dwordx4 v[156:157], off
	s_add_i32 m0, s56, 0x2000
	v_lshl_add_u64 v[164:165], s[68:69], 0, v[132:133]
	s_add_u32 s68, s68, s92
	s_addc_u32 s69, s69, 0
	s_add_i32 s37, s37, s26
	global_load_lds_dwordx4 v[164:165], off
	v_lshl_add_u64 v[238:239], s[68:69], 0, v[134:135]
	s_mov_b32 m0, s37
	v_lshl_add_u64 v[240:241], s[68:69], 0, v[132:133]
	global_load_lds_dwordx4 v[238:239], off
	s_add_i32 m0, s37, 0x2000
	v_lshl_add_u64 v[242:243], s[22:23], 0, v[146:147]
	global_load_lds_dwordx4 v[240:241], off
	s_mov_b32 m0, s45
	v_lshl_add_u64 v[244:245], s[22:23], 0, v[144:145]
	global_load_lds_dwordx4 v[242:243], off
	s_mov_b32 m0, s46
	s_nop 0
	global_load_lds_dwordx4 v[244:245], off
	s_waitcnt vmcnt(8)
	s_waitcnt lgkmcnt(0)
	s_barrier
	s_setprio 1
	s_waitcnt lgkmcnt(0)
	v_mfma_f32_16x16x32_bf16 v[62:65], v[152:155], v[206:209], v[62:65]
	v_mfma_f32_16x16x32_bf16 v[58:61], v[182:185], v[206:209], v[58:61]
	v_mfma_f32_16x16x32_bf16 v[46:49], v[152:155], v[214:217], v[46:49]
	v_mfma_f32_16x16x32_bf16 v[42:45], v[182:185], v[214:217], v[42:45]
	v_mfma_f32_16x16x32_bf16 v[30:33], v[152:155], v[222:225], v[30:33]
	v_mfma_f32_16x16x32_bf16 v[26:29], v[182:185], v[222:225], v[26:29]
	v_mfma_f32_16x16x32_bf16 v[14:17], v[152:155], v[230:233], v[14:17]
	v_mfma_f32_16x16x32_bf16 v[10:13], v[182:185], v[230:233], v[10:13]
	v_mfma_f32_16x16x32_bf16 v[62:65], v[178:181], v[210:213], v[62:65]
	v_mfma_f32_16x16x32_bf16 v[58:61], v[186:189], v[210:213], v[58:61]
	v_mfma_f32_16x16x32_bf16 v[46:49], v[178:181], v[218:221], v[46:49]
	v_mfma_f32_16x16x32_bf16 v[42:45], v[186:189], v[218:221], v[42:45]
	v_mfma_f32_16x16x32_bf16 v[30:33], v[178:181], v[226:229], v[30:33]
	v_mfma_f32_16x16x32_bf16 v[26:29], v[186:189], v[226:229], v[26:29]
	v_mfma_f32_16x16x32_bf16 v[14:17], v[178:181], v[234:237], v[14:17]
	v_mfma_f32_16x16x32_bf16 v[10:13], v[186:189], v[234:237], v[10:13]
	s_setprio 0
	s_setprio 1
	v_mfma_f32_16x16x32_bf16 v[54:57], v[190:193], v[206:209], v[54:57]
	v_mfma_f32_16x16x32_bf16 v[50:53], v[198:201], v[206:209], v[50:53]
	v_mfma_f32_16x16x32_bf16 v[38:41], v[190:193], v[214:217], v[38:41]
	v_mfma_f32_16x16x32_bf16 v[34:37], v[198:201], v[214:217], v[34:37]
	v_mfma_f32_16x16x32_bf16 v[22:25], v[190:193], v[222:225], v[22:25]
	v_mfma_f32_16x16x32_bf16 v[18:21], v[198:201], v[222:225], v[18:21]
	v_mfma_f32_16x16x32_bf16 v[6:9], v[190:193], v[230:233], v[6:9]
	v_mfma_f32_16x16x32_bf16 v[2:5], v[198:201], v[230:233], v[2:5]
	v_mfma_f32_16x16x32_bf16 v[54:57], v[194:197], v[210:213], v[54:57]
	v_mfma_f32_16x16x32_bf16 v[50:53], v[202:205], v[210:213], v[50:53]
	v_mfma_f32_16x16x32_bf16 v[38:41], v[194:197], v[218:221], v[38:41]
	v_mfma_f32_16x16x32_bf16 v[34:37], v[202:205], v[218:221], v[34:37]
	s_setprio 2
	s_barrier
	v_mfma_f32_16x16x32_bf16 v[22:25], v[194:197], v[226:229], v[22:25]
	v_mfma_f32_16x16x32_bf16 v[18:21], v[202:205], v[226:229], v[18:21]
	v_mfma_f32_16x16x32_bf16 v[6:9], v[194:197], v[234:237], v[6:9]
	v_mfma_f32_16x16x32_bf16 v[2:5], v[202:205], v[234:237], v[2:5]
	s_setprio 0
	s_add_i32 s37, 0, 0x18000
	v_add_u32_e32 v162, s37, v159
	s_add_i32 s56, 0, 0x1c000
	ds_read_b128 v[152:155], v162
	ds_read_b128 v[178:181], v162 offset:1024
	ds_read_b128 v[182:185], v162 offset:2048
	ds_read_b128 v[186:189], v162 offset:3072
	v_add_u32_e32 v162, s56, v159
	ds_read_b128 v[190:193], v162
	ds_read_b128 v[194:197], v162 offset:1024
	ds_read_b128 v[198:201], v162 offset:2048
	ds_read_b128 v[202:205], v162 offset:3072
	s_add_u32 s22, s22, s92
	s_addc_u32 s23, s23, 0
	s_mov_b32 m0, s47
	v_lshl_add_u64 v[246:247], s[22:23], 0, v[146:147]
	ds_read_b128 v[206:209], v161 offset:32768
	ds_read_b128 v[210:213], v161 offset:33792
	ds_read_b128 v[214:217], v161 offset:34816
	ds_read_b128 v[218:221], v161 offset:35840
	ds_read_b128 v[222:225], v161 offset:36864
	ds_read_b128 v[226:229], v161 offset:37888
	ds_read_b128 v[230:233], v161 offset:38912
	ds_read_b128 v[234:237], v161 offset:39936
	global_load_lds_dwordx4 v[246:247], off
	v_lshl_add_u64 v[246:247], s[22:23], 0, v[144:145]
	s_mov_b32 m0, s50
	s_nop 0
	global_load_lds_dwordx4 v[246:247], off
	s_waitcnt vmcnt(8)
	s_waitcnt lgkmcnt(0)
	s_barrier
	s_setprio 1
	s_waitcnt lgkmcnt(0)
	v_mfma_f32_16x16x32_bf16 v[126:129], v[152:155], v[206:209], v[126:129]
	v_mfma_f32_16x16x32_bf16 v[122:125], v[182:185], v[206:209], v[122:125]
	v_mfma_f32_16x16x32_bf16 v[110:113], v[152:155], v[214:217], v[110:113]
	v_mfma_f32_16x16x32_bf16 v[106:109], v[182:185], v[214:217], v[106:109]
	v_mfma_f32_16x16x32_bf16 v[94:97], v[152:155], v[222:225], v[94:97]
	v_mfma_f32_16x16x32_bf16 v[90:93], v[182:185], v[222:225], v[90:93]
	v_mfma_f32_16x16x32_bf16 v[78:81], v[152:155], v[230:233], v[78:81]
	v_mfma_f32_16x16x32_bf16 v[74:77], v[182:185], v[230:233], v[74:77]
	v_mfma_f32_16x16x32_bf16 v[126:129], v[178:181], v[210:213], v[126:129]
	v_mfma_f32_16x16x32_bf16 v[122:125], v[186:189], v[210:213], v[122:125]
	v_mfma_f32_16x16x32_bf16 v[110:113], v[178:181], v[218:221], v[110:113]
	v_mfma_f32_16x16x32_bf16 v[106:109], v[186:189], v[218:221], v[106:109]
	v_mfma_f32_16x16x32_bf16 v[94:97], v[178:181], v[226:229], v[94:97]
	v_mfma_f32_16x16x32_bf16 v[90:93], v[186:189], v[226:229], v[90:93]
	v_mfma_f32_16x16x32_bf16 v[78:81], v[178:181], v[234:237], v[78:81]
	v_mfma_f32_16x16x32_bf16 v[74:77], v[186:189], v[234:237], v[74:77]
	s_setprio 0
	s_setprio 1
	v_mfma_f32_16x16x32_bf16 v[118:121], v[190:193], v[206:209], v[118:121]
	v_mfma_f32_16x16x32_bf16 v[114:117], v[198:201], v[206:209], v[114:117]
	v_mfma_f32_16x16x32_bf16 v[102:105], v[190:193], v[214:217], v[102:105]
	v_mfma_f32_16x16x32_bf16 v[98:101], v[198:201], v[214:217], v[98:101]
	v_mfma_f32_16x16x32_bf16 v[86:89], v[190:193], v[222:225], v[86:89]
	v_mfma_f32_16x16x32_bf16 v[82:85], v[198:201], v[222:225], v[82:85]
	v_mfma_f32_16x16x32_bf16 v[70:73], v[190:193], v[230:233], v[70:73]
	v_mfma_f32_16x16x32_bf16 v[66:69], v[198:201], v[230:233], v[66:69]
	v_mfma_f32_16x16x32_bf16 v[118:121], v[194:197], v[210:213], v[118:121]
	v_mfma_f32_16x16x32_bf16 v[114:117], v[202:205], v[210:213], v[114:117]
	v_mfma_f32_16x16x32_bf16 v[102:105], v[194:197], v[218:221], v[102:105]
	v_mfma_f32_16x16x32_bf16 v[98:101], v[202:205], v[218:221], v[98:101]
	s_setprio 2
	s_barrier
	v_mfma_f32_16x16x32_bf16 v[86:89], v[194:197], v[226:229], v[86:89]
	v_mfma_f32_16x16x32_bf16 v[82:85], v[202:205], v[226:229], v[82:85]
	v_mfma_f32_16x16x32_bf16 v[70:73], v[194:197], v[234:237], v[70:73]
	v_mfma_f32_16x16x32_bf16 v[66:69], v[202:205], v[234:237], v[66:69]
	s_setprio 0
	s_add_i32 s22, s37, s26
	v_lshl_add_u64 v[156:157], v[156:157], 0, s[66:67]
	s_mov_b32 m0, s22
	ds_read_b128 v[206:209], v161 offset:49152
	ds_read_b128 v[210:213], v161 offset:50176
	ds_read_b128 v[214:217], v161 offset:51200
	ds_read_b128 v[218:221], v161 offset:52224
	ds_read_b128 v[222:225], v161 offset:53248
	ds_read_b128 v[226:229], v161 offset:54272
	ds_read_b128 v[230:233], v161 offset:55296
	ds_read_b128 v[234:237], v161 offset:56320
	global_load_lds_dwordx4 v[156:157], off
	v_lshl_add_u64 v[156:157], v[164:165], 0, s[66:67]
	s_add_i32 m0, s22, 0x2000
	s_add_i32 s22, s56, s26
	global_load_lds_dwordx4 v[156:157], off
	v_lshl_add_u64 v[156:157], v[238:239], 0, s[66:67]
	s_mov_b32 m0, s22
	s_nop 0
	global_load_lds_dwordx4 v[156:157], off
	v_lshl_add_u64 v[156:157], v[240:241], 0, s[66:67]
	s_add_i32 m0, s22, 0x2000
	s_nop 0
	global_load_lds_dwordx4 v[156:157], off
	v_lshl_add_u64 v[156:157], v[242:243], 0, s[66:67]
	s_mov_b32 m0, s51
	s_nop 0
	global_load_lds_dwordx4 v[156:157], off
	v_lshl_add_u64 v[156:157], v[244:245], 0, s[66:67]
	s_mov_b32 m0, s52
	s_nop 0
	global_load_lds_dwordx4 v[156:157], off
	s_waitcnt vmcnt(8)
	s_waitcnt lgkmcnt(0)
	s_barrier
	s_setprio 1
	s_waitcnt lgkmcnt(0)
	v_mfma_f32_16x16x32_bf16 v[62:65], v[152:155], v[206:209], v[62:65]
	v_mfma_f32_16x16x32_bf16 v[58:61], v[182:185], v[206:209], v[58:61]
	v_mfma_f32_16x16x32_bf16 v[46:49], v[152:155], v[214:217], v[46:49]
	v_mfma_f32_16x16x32_bf16 v[42:45], v[182:185], v[214:217], v[42:45]
	v_mfma_f32_16x16x32_bf16 v[30:33], v[152:155], v[222:225], v[30:33]
	v_mfma_f32_16x16x32_bf16 v[26:29], v[182:185], v[222:225], v[26:29]
	v_mfma_f32_16x16x32_bf16 v[14:17], v[152:155], v[230:233], v[14:17]
	v_mfma_f32_16x16x32_bf16 v[10:13], v[182:185], v[230:233], v[10:13]
	v_mfma_f32_16x16x32_bf16 v[62:65], v[178:181], v[210:213], v[62:65]
	v_mfma_f32_16x16x32_bf16 v[58:61], v[186:189], v[210:213], v[58:61]
	v_mfma_f32_16x16x32_bf16 v[46:49], v[178:181], v[218:221], v[46:49]
	v_mfma_f32_16x16x32_bf16 v[42:45], v[186:189], v[218:221], v[42:45]
	v_mfma_f32_16x16x32_bf16 v[30:33], v[178:181], v[226:229], v[30:33]
	v_mfma_f32_16x16x32_bf16 v[26:29], v[186:189], v[226:229], v[26:29]
	v_mfma_f32_16x16x32_bf16 v[14:17], v[178:181], v[234:237], v[14:17]
	v_mfma_f32_16x16x32_bf16 v[10:13], v[186:189], v[234:237], v[10:13]
	s_setprio 0
	s_setprio 1
	v_mfma_f32_16x16x32_bf16 v[54:57], v[190:193], v[206:209], v[54:57]
	v_mfma_f32_16x16x32_bf16 v[50:53], v[198:201], v[206:209], v[50:53]
	v_mfma_f32_16x16x32_bf16 v[38:41], v[190:193], v[214:217], v[38:41]
	v_mfma_f32_16x16x32_bf16 v[34:37], v[198:201], v[214:217], v[34:37]
	v_mfma_f32_16x16x32_bf16 v[22:25], v[190:193], v[222:225], v[22:25]
	v_mfma_f32_16x16x32_bf16 v[18:21], v[198:201], v[222:225], v[18:21]
	v_mfma_f32_16x16x32_bf16 v[6:9], v[190:193], v[230:233], v[6:9]
	v_mfma_f32_16x16x32_bf16 v[2:5], v[198:201], v[230:233], v[2:5]
	v_mfma_f32_16x16x32_bf16 v[54:57], v[194:197], v[210:213], v[54:57]
	v_mfma_f32_16x16x32_bf16 v[50:53], v[202:205], v[210:213], v[50:53]
	v_mfma_f32_16x16x32_bf16 v[38:41], v[194:197], v[218:221], v[38:41]
	v_mfma_f32_16x16x32_bf16 v[34:37], v[202:205], v[218:221], v[34:37]
	s_setprio 2
	s_barrier
	v_mfma_f32_16x16x32_bf16 v[22:25], v[194:197], v[226:229], v[22:25]
	v_mfma_f32_16x16x32_bf16 v[18:21], v[202:205], v[226:229], v[18:21]
	v_mfma_f32_16x16x32_bf16 v[6:9], v[194:197], v[234:237], v[6:9]
	v_mfma_f32_16x16x32_bf16 v[2:5], v[202:205], v[234:237], v[2:5]
	s_setprio 0
	s_add_u32 s12, s12, 0x100
	s_addc_u32 s13, s13, 0
	s_add_u32 s24, s24, 0x100
	s_addc_u32 s25, s25, 0
	s_cmp_ge_u32 s30, s4
	s_mov_b32 s22, s30
	s_cbranch_scc0 .LBB0_318
	v_lshl_or_b32 v184, s19, 8, v160
	v_ashrrev_i32_e32 v185, 31, v184
	v_lshl_add_u32 v182, s21, 8, v131
	v_ashrrev_i32_e32 v183, 31, v182
	v_lshlrev_b64 v[182:183], 11, v[182:183]
	v_lshl_add_u64 v[182:183], s[78:79], 0, v[182:183]
	v_lshl_add_u64 v[182:183], v[184:185], 1, v[182:183]
	global_load_dwordx4 v[186:189], v[182:183], off
	global_load_dwordx4 v[190:193], v[182:183], off offset:256
	v_lshl_add_u32 v182, s21, 8, v131
	v_add_u32_e32 v182, 16, v182
	v_ashrrev_i32_e32 v183, 31, v182
	v_lshlrev_b64 v[182:183], 11, v[182:183]
	v_lshl_add_u64 v[182:183], s[78:79], 0, v[182:183]
	v_lshl_add_u64 v[182:183], v[184:185], 1, v[182:183]
	global_load_dwordx4 v[194:197], v[182:183], off
	global_load_dwordx4 v[198:201], v[182:183], off offset:256
	v_lshl_add_u32 v182, s21, 8, v131
	v_add_u32_e32 v182, 32, v182
	v_ashrrev_i32_e32 v183, 31, v182
	v_lshlrev_b64 v[182:183], 11, v[182:183]
	v_lshl_add_u64 v[182:183], s[78:79], 0, v[182:183]
	v_lshl_add_u64 v[182:183], v[184:185], 1, v[182:183]
	global_load_dwordx4 v[202:205], v[182:183], off
	global_load_dwordx4 v[206:209], v[182:183], off offset:256
	v_lshl_add_u32 v182, s21, 8, v131
	v_add_u32_e32 v182, 48, v182
	v_ashrrev_i32_e32 v183, 31, v182
	v_lshlrev_b64 v[182:183], 11, v[182:183]
	v_lshl_add_u64 v[182:183], s[78:79], 0, v[182:183]
	v_lshl_add_u64 v[182:183], v[184:185], 1, v[182:183]
	global_load_dwordx4 v[210:213], v[182:183], off
	global_load_dwordx4 v[214:217], v[182:183], off offset:256
	v_lshl_add_u32 v182, s21, 8, v131
	v_add_u32_e32 v182, 0x80, v182
	v_ashrrev_i32_e32 v183, 31, v182
	v_lshlrev_b64 v[182:183], 11, v[182:183]
	v_lshl_add_u64 v[182:183], s[78:79], 0, v[182:183]
	v_lshl_add_u64 v[182:183], v[184:185], 1, v[182:183]
	global_load_dwordx4 v[218:221], v[182:183], off
	global_load_dwordx4 v[222:225], v[182:183], off offset:256
	v_lshl_add_u32 v182, s21, 8, v131
	v_add_u32_e32 v182, 0x90, v182
	v_ashrrev_i32_e32 v183, 31, v182
	v_lshlrev_b64 v[182:183], 11, v[182:183]
	v_lshl_add_u64 v[182:183], s[78:79], 0, v[182:183]
	v_lshl_add_u64 v[182:183], v[184:185], 1, v[182:183]
	global_load_dwordx4 v[226:229], v[182:183], off
	global_load_dwordx4 v[230:233], v[182:183], off offset:256
	v_lshl_add_u32 v182, s21, 8, v131
	v_add_u32_e32 v182, 0xa0, v182
	v_ashrrev_i32_e32 v183, 31, v182
	v_lshlrev_b64 v[182:183], 11, v[182:183]
	v_lshl_add_u64 v[182:183], s[78:79], 0, v[182:183]
	v_lshl_add_u64 v[182:183], v[184:185], 1, v[182:183]
	global_load_dwordx4 v[234:237], v[182:183], off
	global_load_dwordx4 v[238:241], v[182:183], off offset:256
	v_lshl_add_u32 v182, s21, 8, v131
	v_add_u32_e32 v182, 0xb0, v182
	v_ashrrev_i32_e32 v183, 31, v182
	v_lshlrev_b64 v[182:183], 11, v[182:183]
	v_lshl_add_u64 v[182:183], s[78:79], 0, v[182:183]
	v_lshl_add_u64 v[182:183], v[184:185], 1, v[182:183]
	global_load_dwordx4 v[242:245], v[182:183], off
	global_load_dwordx4 v[246:249], v[182:183], off offset:256
	s_and_b64 vcc, exec, s[96:97]
	s_cbranch_vccz .LBB0_321
	s_barrier

.LBB0_348:
	s_or_b64 exec, exec, s[6:7]
	s_movk_i32 s4, 0x800
	v_cmp_gt_i32_e32 vcc, s4, v130
	s_and_saveexec_b64 s[6:7], vcc
	s_cbranch_execz .LBB0_353
	s_lshl_b32 s4, s40, 18
	s_add_u32 s4, s84, s4
	v_readlane_b32 s8, v254, 7
	s_addc_u32 s5, s85, 0
	s_lshl_b32 s8, s8, 1
	s_add_u32 s4, s4, s8
	v_readlane_b32 s8, v254, 9
	s_addc_u32 s5, s5, 0
	s_lshl_b32 s8, s8, 1
	s_add_u32 s4, s4, s8
	v_lshlrev_b32_e32 v5, 4, v130
	s_addc_u32 s5, s5, 0
	v_and_b32_e32 v134, 0x70, v5
	s_waitcnt lgkmcnt(0)
	v_lshl_add_u64 v[2:3], s[4:5], 0, v[134:135]
	v_add_u32_e32 v4, 0, v134
	v_ashrrev_i32_e32 v12, 3, v130
	v_mov_b32_e32 v13, 0
	v_lshlrev_b64 v[8:9], 9, v[12:13]
	v_lshl_add_u64 v[8:9], v[2:3], 0, v[8:9]
	v_mad_u32_u24 v226, v12, s29, v4
	s_mov_b64 s[8:9], 0x8000
	global_load_dwordx4 v[178:181], v[8:9], off
	v_lshl_add_u64 v[8:9], v[8:9], 0, s[8:9]
	global_load_dwordx4 v[182:185], v[8:9], off
	v_lshl_add_u64 v[8:9], v[8:9], 0, s[8:9]
	global_load_dwordx4 v[186:189], v[8:9], off
	v_lshl_add_u64 v[8:9], v[8:9], 0, s[8:9]
	global_load_dwordx4 v[190:193], v[8:9], off
	s_lshl_b32 s4, s35, 18
	v_readlane_b32 s5, v254, 8
	s_or_b32 s4, s4, s5
	s_add_u32 s4, s31, s4
	s_addc_u32 s5, s59, 0
	v_readlane_b32 s8, v254, 10
	s_add_u32 s4, s4, s8
	s_addc_u32 s5, s5, 0
	v_and_b32_e32 v134, 0x1f0, v5
	v_lshl_add_u64 v[2:3], s[4:5], 0, v[134:135]
	v_add_u32_e32 v4, 0, v134
	v_ashrrev_i32_e32 v10, 5, v130
	v_mov_b32_e32 v11, 0
	v_lshlrev_b64 v[6:7], 9, v[10:11]
	v_lshl_add_u64 v[6:7], v[2:3], 0, v[6:7]
	v_mad_u32_u24 v227, v10, s36, v4
	s_mov_b64 s[8:9], 0x2000
	global_load_dwordx4 v[194:197], v[6:7], off
	v_lshl_add_u64 v[6:7], v[6:7], 0, s[8:9]
	global_load_dwordx4 v[198:201], v[6:7], off
	v_lshl_add_u64 v[6:7], v[6:7], 0, s[8:9]
	global_load_dwordx4 v[202:205], v[6:7], off
	v_lshl_add_u64 v[6:7], v[6:7], 0, s[8:9]
	global_load_dwordx4 v[206:209], v[6:7], off
	s_waitcnt vmcnt(7)
	ds_write_b128 v226, v[178:181]
	s_waitcnt vmcnt(6)
	ds_write_b128 v226, v[182:185] offset:9216
	s_waitcnt vmcnt(5)
	ds_write_b128 v226, v[186:189] offset:18432
	s_waitcnt vmcnt(4)
	ds_write_b128 v226, v[190:193] offset:27648
	s_waitcnt vmcnt(3)
	ds_write_b128 v227, v[194:197] offset:36864
	s_waitcnt vmcnt(2)
	ds_write_b128 v227, v[198:201] offset:45312
	s_waitcnt vmcnt(1)
	ds_write_b128 v227, v[202:205] offset:53760
	s_waitcnt vmcnt(0)
	ds_write_b128 v227, v[206:209] offset:62208
